# SB tile loop and MLA band loop: 53 more v_max(x,x) canonicalisations removed (readers take x directly)
# speedup vs baseline: 1.0048x; 1.0016x over previous
; #define LAS __attribute__((address_space(3)))
; __device__ __forceinline__ int crow(int r, int hi) { return (r & 3) + 8 * (r >> 2) + 4 * hi; }
; #define MFMA32(a, b, c) __builtin_amdgcn_mfma_f32_32x32x16_bf16((a), (b), (c), 0, 0, 0)
; template <bool MASK> __device__ __forceinline__ void sm_tile(f32x16& p0, f32x16& p1, float& mrun, float& lrun, f32x16& o0, f32x16& o1, LAS float* wsf, int kv0, int qpos, int q32, int hi) {
;     if (MASK) {
; #pragma unroll
;         for (int r = 0; r < 16; ++r) { if (kv0 + crow(r, hi) > qpos) p0[r] = -INFINITY; if (kv0 + 32 + crow(r, hi) > qpos) p1[r] = -INFINITY; } }
;     float rm = fmaxf(p0[0], p1[0]);
; #pragma unroll
;     for (int r = 1; r < 16; ++r) rm = fmaxf(rm, fmaxf(p0[r], p1[r]));
;     rm = fmaxf(rm, xhalf(rm, hi));
;     if (__any(rm > mrun + 8.0f)) {
; template <bool MASK> __device__ __forceinline__ void sm_iter(int var, SmState& st, const bf16x8 (&qr)[6], const LAS unsigned char* kb, const LAS unsigned char* vb, LAS float* wsf, int kv0, int qpos, int q32, int hi) {
;     ...
;     for (int d0 = 0; d0 < ND; ++d0) { kf[2 * d0] = *(const LAS bf16x8*)(kb + d0 * 32); kf[2 * d0 + 1] = *(const LAS bf16x8*)(kb + 32 * KP + d0 * 32); }
;     __builtin_amdgcn_sched_barrier(0);
; #pragma unroll
;     for (int d0 = 0; d0 < ND; ++d0) { p0 = MFMA32(kf[2 * d0], qr[d0], p0); p1 = MFMA32(kf[2 * d0 + 1], qr[d0], p1); }
.LBB0_63:
	s_add_i32 s4, s0, -1
	s_and_b32 s4, s4, 1
	s_mul_i32 s18, s4, 0x6800
	v_add_u32_e32 v48, s18, v162
	s_mul_i32 s18, s4, 0x4200
	v_add_u32_e32 v160, v48, v153
	v_add_u32_e32 v48, s18, v163
	s_cmp_gt_i32 s20, s5
	v_add_u32_e32 v158, 0xd000, v48
	v_add_u32_e32 v159, 0xf000, v48
	s_cbranch_scc1 .LBB0_68
	ds_read_b128 v[48:51], v160
	ds_read_b128 v[116:119], v160 offset:32
	ds_read_b128 v[52:55], v160 offset:6656
	ds_read_b128 v[120:123], v160 offset:6688
	ds_read_b128 v[124:127], v160 offset:64
	ds_read_b128 v[128:131], v160 offset:96
	ds_read_b128 v[132:135], v160 offset:6720
	ds_read_b128 v[136:139], v160 offset:6752
	ds_read_b128 v[140:143], v160 offset:128
	ds_read_b128 v[172:175], v160 offset:160
	ds_read_b128 v[144:147], v160 offset:6784
	ds_read_b128 v[176:179], v160 offset:6816
	s_waitcnt vmcnt(3) lgkmcnt(11)
	v_mfma_f32_32x32x16_bf16 v[64:79], v[48:51], v[84:87], 0
	s_waitcnt lgkmcnt(9)
	v_mfma_f32_32x32x16_bf16 v[48:63], v[52:55], v[84:87], 0
	s_waitcnt vmcnt(2)
	v_mfma_f32_32x32x16_bf16 v[64:79], v[116:119], v[88:91], v[64:79]
	s_waitcnt lgkmcnt(8)
	v_mfma_f32_32x32x16_bf16 v[48:63], v[120:123], v[88:91], v[48:63]
	s_waitcnt vmcnt(1) lgkmcnt(7)
	v_mfma_f32_32x32x16_bf16 v[64:79], v[124:127], v[92:95], v[64:79]
	s_waitcnt lgkmcnt(5)
	v_mfma_f32_32x32x16_bf16 v[48:63], v[132:135], v[92:95], v[48:63]
	s_waitcnt vmcnt(0)
	v_mfma_f32_32x32x16_bf16 v[64:79], v[128:131], v[96:99], v[64:79]
	s_waitcnt lgkmcnt(4)
	v_mfma_f32_32x32x16_bf16 v[48:63], v[136:139], v[96:99], v[48:63]
	s_waitcnt lgkmcnt(3)
	v_mfma_f32_32x32x16_bf16 v[64:79], v[140:143], v[100:103], v[64:79]
	s_waitcnt lgkmcnt(1)
	v_mfma_f32_32x32x16_bf16 v[48:63], v[144:147], v[100:103], v[48:63]
	ds_read2_b64 v[144:147], v158 offset1:2
	ds_read2_b64 v[136:139], v158 offset0:4 offset1:6
	ds_read2_b64 v[140:143], v159 offset0:32 offset1:34
	ds_read2_b64 v[132:135], v159 offset0:36 offset1:38
	ds_read2_b64 v[128:131], v158 offset0:8 offset1:10
	ds_read2_b64 v[124:127], v159 offset0:40 offset1:42
	ds_read2_b64 v[120:123], v158 offset0:12 offset1:14
	ds_read2_b64 v[116:119], v159 offset0:44 offset1:46
	v_mfma_f32_32x32x16_bf16 v[64:79], v[172:175], v[104:107], v[64:79]
	s_waitcnt lgkmcnt(8)
	v_mfma_f32_32x32x16_bf16 v[48:63], v[176:179], v[104:107], v[48:63]
	v_cmp_le_i32_e32 vcc, v164, v1
	s_nop 8
	v_cndmask_b32_e32 v177, v241, v64, vcc
	v_add_u32_e32 v64, 32, v164
	v_cmp_le_i32_e32 vcc, v64, v1
	s_nop 1
	v_cndmask_b32_e32 v178, v241, v48, vcc
	v_add_u32_e32 v48, 1, v164
	v_cmp_le_i32_e32 vcc, v48, v1
	v_add_u32_e32 v48, 33, v164
	s_nop 0
	v_cndmask_b32_e32 v179, v241, v65, vcc
	v_cmp_le_i32_e32 vcc, v48, v1
	v_add_u32_e32 v48, 2, v164
	s_nop 0
	v_cndmask_b32_e32 v180, v241, v49, vcc
	v_cmp_le_i32_e32 vcc, v48, v1
	v_add_u32_e32 v48, 34, v164
	v_add_u32_e32 v49, 27, v164
	v_cndmask_b32_e32 v173, v241, v66, vcc
	v_cmp_le_i32_e32 vcc, v48, v1
	v_add_u32_e32 v48, 3, v164
	s_nop 0
	v_cndmask_b32_e32 v174, v241, v50, vcc
	v_cmp_le_i32_e32 vcc, v48, v1
	v_add_u32_e32 v48, 35, v164
	s_nop 0
	v_cndmask_b32_e32 v175, v241, v67, vcc
	v_cmp_le_i32_e32 vcc, v48, v1
	v_add_u32_e32 v48, 8, v164
	s_nop 0
	v_cndmask_b32_e32 v176, v241, v51, vcc
	v_cmp_le_i32_e32 vcc, v48, v1
	v_add_u32_e32 v48, 40, v164
	s_nop 0
	v_cndmask_b32_e32 v165, v241, v68, vcc
	v_cmp_le_i32_e32 vcc, v48, v1
	v_add_u32_e32 v48, 9, v164
	s_nop 0
	v_cndmask_b32_e32 v166, v241, v52, vcc
	v_cmp_le_i32_e32 vcc, v48, v1
	v_add_u32_e32 v48, 41, v164
	s_nop 0
	v_cndmask_b32_e32 v167, v241, v69, vcc
	v_cmp_le_i32_e32 vcc, v48, v1
	v_add_u32_e32 v48, 10, v164
	s_nop 0
	v_cndmask_b32_e32 v172, v241, v53, vcc
	v_cmp_le_i32_e32 vcc, v48, v1
	v_add_u32_e32 v48, 42, v164
	s_nop 0
	v_cndmask_b32_e32 v68, v241, v70, vcc
	v_cmp_le_i32_e32 vcc, v48, v1
	v_add_u32_e32 v48, 11, v164
	s_nop 0
	v_cndmask_b32_e32 v69, v241, v54, vcc
	v_cmp_le_i32_e32 vcc, v48, v1
	v_add_u32_e32 v48, 43, v164
	s_nop 0
	v_cndmask_b32_e32 v70, v241, v71, vcc
	v_cmp_le_i32_e32 vcc, v48, v1
	v_add_u32_e32 v48, 16, v164
	s_nop 0
	v_cndmask_b32_e32 v71, v241, v55, vcc
	v_cmp_le_i32_e32 vcc, v48, v1
	v_add_u32_e32 v48, 48, v164
	s_nop 0
	v_cndmask_b32_e32 v64, v241, v72, vcc
	v_cmp_le_i32_e32 vcc, v48, v1
	v_add_u32_e32 v48, 17, v164
	s_nop 0
	v_cndmask_b32_e32 v65, v241, v56, vcc
	v_cmp_le_i32_e32 vcc, v48, v1
	v_add_u32_e32 v48, 49, v164
	s_nop 0
	v_cndmask_b32_e32 v66, v241, v73, vcc
	v_cmp_le_i32_e32 vcc, v48, v1
	v_add_u32_e32 v48, 18, v164
	s_nop 0
	v_cndmask_b32_e32 v67, v241, v57, vcc
	v_cmp_le_i32_e32 vcc, v48, v1
	v_add_u32_e32 v48, 50, v164
	s_nop 0
	v_cndmask_b32_e32 v56, v241, v74, vcc
	v_cmp_le_i32_e32 vcc, v48, v1
	v_add_u32_e32 v48, 19, v164
	s_nop 0
	v_cndmask_b32_e32 v57, v241, v58, vcc
	v_cmp_le_i32_e32 vcc, v48, v1
	v_add_u32_e32 v48, 51, v164
	s_nop 0
	v_cndmask_b32_e32 v58, v241, v75, vcc
	v_cmp_le_i32_e32 vcc, v48, v1
	v_add_u32_e32 v48, 24, v164
	s_nop 0
	v_cndmask_b32_e32 v59, v241, v59, vcc
	v_cmp_le_i32_e32 vcc, v48, v1
	v_add_u32_e32 v48, 56, v164
	s_nop 0
	v_cndmask_b32_e32 v53, v241, v76, vcc
	v_cmp_le_i32_e32 vcc, v48, v1
	v_add_u32_e32 v48, 25, v164
	s_nop 0
	v_cndmask_b32_e32 v54, v241, v60, vcc
	v_cmp_le_i32_e32 vcc, v48, v1
	v_add_u32_e32 v48, 57, v164
	v_max_f32_e32 v60, v180, v180
	v_cndmask_b32_e32 v55, v241, v77, vcc
	v_cmp_le_i32_e32 vcc, v48, v1
	v_add_u32_e32 v48, 26, v164
	s_nop 0
	v_cndmask_b32_e32 v52, v241, v61, vcc
	v_cmp_le_i32_e32 vcc, v48, v1
	v_add_u32_e32 v48, 58, v164
	v_max_f32_e32 v61, v179, v179
	v_cndmask_b32_e32 v50, v241, v78, vcc
	v_cmp_le_i32_e32 vcc, v48, v1
	v_max_f32_e32 v60, v61, v60
	v_max_f32_e32 v61, v174, v174
	v_cndmask_b32_e32 v48, v241, v62, vcc
	v_cmp_le_i32_e32 vcc, v49, v1
	v_add_u32_e32 v49, 59, v164
	v_max_f32_e32 v62, v173, v173
	v_cndmask_b32_e32 v51, v241, v79, vcc
	v_cmp_le_i32_e32 vcc, v49, v1
	v_max_f32_e32 v61, v62, v61
	v_max_f32_e32 v62, v176, v176
	v_cndmask_b32_e32 v49, v241, v63, vcc
	v_max3_f32 v60, v177, v178, v60
	v_max_f32_e32 v62, v175, v62
	v_max3_f32 v60, v60, v61, v62
	v_max_f32_e32 v61, v165, v166
	v_max_f32_e32 v62, v167, v172
	v_max3_f32 v60, v60, v61, v62
	v_max_f32_e32 v61, v68, v69
	v_max_f32_e32 v62, v70, v71
	v_max3_f32 v60, v60, v61, v62
	v_max_f32_e32 v61, v64, v65
	v_max_f32_e32 v62, v66, v67
	v_max3_f32 v60, v60, v61, v62
	v_max_f32_e32 v61, v56, v57
	v_max_f32_e32 v62, v58, v59
	v_max3_f32 v60, v60, v61, v62
	v_max_f32_e32 v61, v53, v54
	v_max_f32_e32 v62, v55, v52
	v_max3_f32 v60, v60, v61, v62
	v_max_f32_e32 v61, v50, v48
	v_max_f32_e32 v63, v51, v51
	v_max_f32_e32 v62, v63, v49
	v_max3_f32 v60, v60, v61, v62
	v_mov_b32_e32 v61, v60
	v_mov_b32_e32 v62, v60
	s_nop 1
	v_permlane32_swap_b32_e32 v61, v62
	v_cndmask_b32_e64 v61, v61, v62, s[40:41]
	v_max_f32_e32 v61, v61, v61
	v_max_f32_e32 v60, v60, v61
	v_add_f32_e32 v61, 0x41000000, v171
	v_cmp_gt_f32_e32 vcc, v60, v61
	s_cbranch_vccz .LBB0_70
; __device__ __forceinline__ int crow(int r, int hi) { return (r & 3) + 8 * (r >> 2) + 4 * hi; }
; __device__ __forceinline__ float ex2(float x) { return __builtin_amdgcn_exp2f(x); }
; template <bool MASK> __device__ __forceinline__ void sm_tile(f32x16& p0, f32x16& p1, float& mrun, float& lrun, f32x16& o0, f32x16& o1, LAS float* wsf, int kv0, int qpos, int q32, int hi) {
;     ...
;     if (__any(rm > mrun + 8.0f)) {
;         const float mnew = fmaxf(mrun, rm), alpha = ex2(mrun - mnew); mrun = mnew; lrun *= alpha;
;         if (hi == 0) wsf[q32] = alpha;
;         __builtin_amdgcn_fence(__ATOMIC_RELEASE, "wavefront"); asm volatile("s_waitcnt lgkmcnt(0)" ::: "memory");
; #pragma unroll
;         for (int r = 0; r < 16; ++r) { const float al = wsf[crow(r, hi)]; o0[r] *= al; o1[r] *= al; }
	v_max_f32_e32 v60, v60, v60
	v_max_f32_e32 v61, v171, v171
	v_max_f32_e32 v161, v61, v60
	v_sub_f32_e32 v60, v171, v161
	v_exp_f32_e32 v60, v60
	s_and_saveexec_b64 s[18:19], s[40:41]
	ds_write_b32 v149, v60
	s_or_b64 exec, exec, s[18:19]
	s_waitcnt lgkmcnt(0)
	v_add_u32_e32 v171, s25, v148
	v_mul_f32_e32 v170, v170, v60
	ds_read_b128 v[60:63], v171
	ds_read_b128 v[72:75], v171 offset:32
	ds_read_b128 v[76:79], v171 offset:64
	ds_read_b128 v[182:185], v171 offset:96
	s_waitcnt lgkmcnt(3)
	v_pk_mul_f32 v[18:19], v[18:19], v[62:63]
	s_waitcnt lgkmcnt(2)
	v_pk_mul_f32 v[20:21], v[20:21], v[72:73]
	s_waitcnt lgkmcnt(1)
	v_pk_mul_f32 v[24:25], v[24:25], v[76:77]
	s_waitcnt lgkmcnt(0)
	v_pk_mul_f32 v[28:29], v[28:29], v[182:183]
	v_pk_mul_f32 v[30:31], v[30:31], v[184:185]
	v_pk_mul_f32 v[26:27], v[26:27], v[78:79]
	v_pk_mul_f32 v[22:23], v[22:23], v[74:75]
	v_pk_mul_f32 v[16:17], v[16:17], v[60:61]
	v_pk_mul_f32 v[44:45], v[44:45], v[182:183]
	v_pk_mul_f32 v[40:41], v[40:41], v[76:77]
	v_pk_mul_f32 v[36:37], v[36:37], v[72:73]
	v_pk_mul_f32 v[46:47], v[46:47], v[184:185]
	v_pk_mul_f32 v[42:43], v[42:43], v[78:79]
	v_pk_mul_f32 v[38:39], v[38:39], v[74:75]
	v_pk_mul_f32 v[34:35], v[34:35], v[62:63]
	v_pk_mul_f32 v[32:33], v[32:33], v[60:61]
	s_branch .LBB0_71

; #define LAS __attribute__((address_space(3)))
; __device__ __forceinline__ int crow(int r, int hi) { return (r & 3) + 8 * (r >> 2) + 4 * hi; }
; #define MFMA32(a, b, c) __builtin_amdgcn_mfma_f32_32x32x16_bf16((a), (b), (c), 0, 0, 0)
; template <bool MASK> __device__ __forceinline__ void sm_tile(f32x16& p0, f32x16& p1, float& mrun, float& lrun, f32x16& o0, f32x16& o1, LAS float* wsf, int kv0, int qpos, int q32, int hi) {
;     if (MASK) {
; #pragma unroll
;         for (int r = 0; r < 16; ++r) { if (kv0 + crow(r, hi) > qpos) p0[r] = -INFINITY; if (kv0 + 32 + crow(r, hi) > qpos) p1[r] = -INFINITY; } }
;     float rm = fmaxf(p0[0], p1[0]);
; #pragma unroll
;     for (int r = 1; r < 16; ++r) rm = fmaxf(rm, fmaxf(p0[r], p1[r]));
;     rm = fmaxf(rm, xhalf(rm, hi));
;     if (__any(rm > mrun + 8.0f)) {
; template <bool MASK> __device__ __forceinline__ void sm_iter(int var, SmState& st, const bf16x8 (&qr)[6], const LAS unsigned char* kb, const LAS unsigned char* vb, LAS float* wsf, int kv0, int qpos, int q32, int hi) {
;     ...
;     for (int d0 = 0; d0 < ND; ++d0) { kf[2 * d0] = *(const LAS bf16x8*)(kb + d0 * 32); kf[2 * d0 + 1] = *(const LAS bf16x8*)(kb + 32 * KP + d0 * 32); }
;     __builtin_amdgcn_sched_barrier(0);
; #pragma unroll
;     for (int d0 = 0; d0 < ND; ++d0) { p0 = MFMA32(kf[2 * d0], qr[d0], p0); p1 = MFMA32(kf[2 * d0 + 1], qr[d0], p1); }
.LBB0_72:
	ds_read_b128 v[48:51], v160 offset:13312
	ds_read_b128 v[116:119], v160 offset:13344
	ds_read_b128 v[52:55], v160 offset:19968
	ds_read_b128 v[120:123], v160 offset:20000
	ds_read_b128 v[124:127], v160 offset:13376
	ds_read_b128 v[128:131], v160 offset:13408
	ds_read_b128 v[132:135], v160 offset:20032
	ds_read_b128 v[136:139], v160 offset:20064
	ds_read_b128 v[140:143], v160 offset:13440
	ds_read_b128 v[172:175], v160 offset:13472
	ds_read_b128 v[144:147], v160 offset:20096
	ds_read_b128 v[176:179], v160 offset:20128
	s_waitcnt vmcnt(3) lgkmcnt(11)
	v_mfma_f32_32x32x16_bf16 v[64:79], v[48:51], v[84:87], 0
	s_waitcnt lgkmcnt(9)
	v_mfma_f32_32x32x16_bf16 v[48:63], v[52:55], v[84:87], 0
	s_waitcnt vmcnt(2)
	v_mfma_f32_32x32x16_bf16 v[64:79], v[116:119], v[88:91], v[64:79]
	s_waitcnt lgkmcnt(8)
	v_mfma_f32_32x32x16_bf16 v[48:63], v[120:123], v[88:91], v[48:63]
	s_waitcnt vmcnt(1) lgkmcnt(7)
	v_mfma_f32_32x32x16_bf16 v[64:79], v[124:127], v[92:95], v[64:79]
	s_waitcnt lgkmcnt(5)
	v_mfma_f32_32x32x16_bf16 v[48:63], v[132:135], v[92:95], v[48:63]
	s_waitcnt vmcnt(0)
	v_mfma_f32_32x32x16_bf16 v[64:79], v[128:131], v[96:99], v[64:79]
	s_waitcnt lgkmcnt(4)
	v_mfma_f32_32x32x16_bf16 v[48:63], v[136:139], v[96:99], v[48:63]
	s_waitcnt lgkmcnt(3)
	v_mfma_f32_32x32x16_bf16 v[64:79], v[140:143], v[100:103], v[64:79]
	s_waitcnt lgkmcnt(1)
	v_mfma_f32_32x32x16_bf16 v[48:63], v[144:147], v[100:103], v[48:63]
	ds_read2_b64 v[144:147], v158 offset0:16 offset1:18
	ds_read2_b64 v[136:139], v158 offset0:20 offset1:22
	ds_read2_b64 v[140:143], v159 offset0:48 offset1:50
	ds_read2_b64 v[132:135], v159 offset0:52 offset1:54
	ds_read2_b64 v[128:131], v158 offset0:24 offset1:26
	ds_read2_b64 v[124:127], v159 offset0:56 offset1:58
	ds_read2_b64 v[120:123], v158 offset0:28 offset1:30
	ds_read2_b64 v[116:119], v159 offset0:60 offset1:62
	v_mfma_f32_32x32x16_bf16 v[64:79], v[172:175], v[104:107], v[64:79]
	s_waitcnt lgkmcnt(8)
	v_mfma_f32_32x32x16_bf16 v[48:63], v[176:179], v[104:107], v[48:63]
	v_add_u32_e32 v158, 64, v164
	v_cmp_le_i32_e32 vcc, v158, v1
	s_nop 7
	v_cndmask_b32_e32 v174, v241, v64, vcc
	v_add_u32_e32 v64, 0x60, v164
	v_cmp_le_i32_e32 vcc, v64, v1
	s_nop 1
	v_cndmask_b32_e32 v175, v241, v48, vcc
	v_add_u32_e32 v48, 0x41, v164
	v_cmp_le_i32_e32 vcc, v48, v1
	v_add_u32_e32 v48, 0x61, v164
	s_nop 0
	v_cndmask_b32_e32 v176, v241, v65, vcc
	v_cmp_le_i32_e32 vcc, v48, v1
	v_add_u32_e32 v48, 0x42, v164
	s_nop 0
	v_cndmask_b32_e32 v177, v241, v49, vcc
	v_cmp_le_i32_e32 vcc, v48, v1
	v_add_u32_e32 v48, 0x62, v164
	v_add_u32_e32 v49, 0x5b, v164
	v_cndmask_b32_e32 v166, v241, v66, vcc
	v_cmp_le_i32_e32 vcc, v48, v1
	v_add_u32_e32 v48, 0x43, v164
	s_nop 0
	v_cndmask_b32_e32 v167, v241, v50, vcc
	v_cmp_le_i32_e32 vcc, v48, v1
	v_add_u32_e32 v48, 0x63, v164
	s_nop 0
	v_cndmask_b32_e32 v172, v241, v67, vcc
	v_cmp_le_i32_e32 vcc, v48, v1
	v_add_u32_e32 v48, 0x48, v164
	s_nop 0
	v_cndmask_b32_e32 v173, v241, v51, vcc
	v_cmp_le_i32_e32 vcc, v48, v1
	v_add_u32_e32 v48, 0x68, v164
	s_nop 0
	v_cndmask_b32_e32 v158, v241, v68, vcc
	v_cmp_le_i32_e32 vcc, v48, v1
	v_add_u32_e32 v48, 0x49, v164
	s_nop 0
	v_cndmask_b32_e32 v159, v241, v52, vcc
	v_cmp_le_i32_e32 vcc, v48, v1
	v_add_u32_e32 v48, 0x69, v164
	s_nop 0
	v_cndmask_b32_e32 v160, v241, v69, vcc
	v_cmp_le_i32_e32 vcc, v48, v1
	v_add_u32_e32 v48, 0x4a, v164
	s_nop 0
	v_cndmask_b32_e32 v165, v241, v53, vcc
	v_cmp_le_i32_e32 vcc, v48, v1
	v_add_u32_e32 v48, 0x6a, v164
	s_nop 0
	v_cndmask_b32_e32 v68, v241, v70, vcc
	v_cmp_le_i32_e32 vcc, v48, v1
	v_add_u32_e32 v48, 0x4b, v164
	s_nop 0
	v_cndmask_b32_e32 v69, v241, v54, vcc
	v_cmp_le_i32_e32 vcc, v48, v1
	v_add_u32_e32 v48, 0x6b, v164
	s_nop 0
	v_cndmask_b32_e32 v70, v241, v71, vcc
	v_cmp_le_i32_e32 vcc, v48, v1
	v_add_u32_e32 v48, 0x50, v164
	s_nop 0
	v_cndmask_b32_e32 v71, v241, v55, vcc
	v_cmp_le_i32_e32 vcc, v48, v1
	v_add_u32_e32 v48, 0x70, v164
	s_nop 0
	v_cndmask_b32_e32 v64, v241, v72, vcc
	v_cmp_le_i32_e32 vcc, v48, v1
	v_add_u32_e32 v48, 0x51, v164
	s_nop 0
	v_cndmask_b32_e32 v65, v241, v56, vcc
	v_cmp_le_i32_e32 vcc, v48, v1
	v_add_u32_e32 v48, 0x71, v164
	s_nop 0
	v_cndmask_b32_e32 v66, v241, v73, vcc
	v_cmp_le_i32_e32 vcc, v48, v1
	v_add_u32_e32 v48, 0x52, v164
	s_nop 0
	v_cndmask_b32_e32 v67, v241, v57, vcc
	v_cmp_le_i32_e32 vcc, v48, v1
	v_add_u32_e32 v48, 0x72, v164
	s_nop 0
	v_cndmask_b32_e32 v56, v241, v74, vcc
	v_cmp_le_i32_e32 vcc, v48, v1
	v_add_u32_e32 v48, 0x53, v164
	s_nop 0
	v_cndmask_b32_e32 v57, v241, v58, vcc
	v_cmp_le_i32_e32 vcc, v48, v1
	v_add_u32_e32 v48, 0x73, v164
	s_nop 0
	v_cndmask_b32_e32 v58, v241, v75, vcc
	v_cmp_le_i32_e32 vcc, v48, v1
	v_add_u32_e32 v48, 0x58, v164
	s_nop 0
	v_cndmask_b32_e32 v59, v241, v59, vcc
	v_cmp_le_i32_e32 vcc, v48, v1
	v_add_u32_e32 v48, 0x78, v164
	s_nop 0
	v_cndmask_b32_e32 v53, v241, v76, vcc
	v_cmp_le_i32_e32 vcc, v48, v1
	v_add_u32_e32 v48, 0x59, v164
	s_nop 0
	v_cndmask_b32_e32 v54, v241, v60, vcc
	v_cmp_le_i32_e32 vcc, v48, v1
	v_add_u32_e32 v48, 0x79, v164
	v_max_f32_e32 v60, v177, v177
	v_cndmask_b32_e32 v55, v241, v77, vcc
	v_cmp_le_i32_e32 vcc, v48, v1
	v_add_u32_e32 v48, 0x5a, v164
	s_nop 0
	v_cndmask_b32_e32 v52, v241, v61, vcc
	v_cmp_le_i32_e32 vcc, v48, v1
	v_add_u32_e32 v48, 0x7a, v164
	v_max_f32_e32 v61, v176, v176
	v_cndmask_b32_e32 v50, v241, v78, vcc
	v_cmp_le_i32_e32 vcc, v48, v1
	v_max_f32_e32 v60, v61, v60
	v_max_f32_e32 v61, v167, v167
	v_cndmask_b32_e32 v48, v241, v62, vcc
	v_cmp_le_i32_e32 vcc, v49, v1
	v_add_u32_e32 v49, 0x7b, v164
	v_max_f32_e32 v62, v166, v166
	v_cndmask_b32_e32 v51, v241, v79, vcc
	v_cmp_le_i32_e32 vcc, v49, v1
	v_max_f32_e32 v61, v62, v61
	v_max_f32_e32 v62, v173, v173
	v_cndmask_b32_e32 v49, v241, v63, vcc
	v_max3_f32 v60, v174, v175, v60
	v_max_f32_e32 v62, v172, v62
	v_max3_f32 v60, v60, v61, v62
	v_max_f32_e32 v61, v158, v159
	v_max_f32_e32 v62, v160, v165
	v_max3_f32 v60, v60, v61, v62
	v_max_f32_e32 v61, v68, v69
	v_max_f32_e32 v62, v70, v71
	v_max3_f32 v60, v60, v61, v62
	v_max_f32_e32 v61, v64, v65
	v_max_f32_e32 v62, v66, v67
	v_max3_f32 v60, v60, v61, v62
	v_max_f32_e32 v61, v56, v57
	v_max_f32_e32 v62, v58, v59
	v_max3_f32 v60, v60, v61, v62
	v_max_f32_e32 v61, v53, v54
	v_max_f32_e32 v62, v55, v52
	v_max3_f32 v60, v60, v61, v62
	v_max_f32_e32 v61, v50, v48
	v_max_f32_e32 v63, v51, v51
	v_max_f32_e32 v62, v63, v49
	v_max3_f32 v60, v60, v61, v62
	v_mov_b32_e32 v61, v60
	v_mov_b32_e32 v62, v60
	s_nop 1
	v_permlane32_swap_b32_e32 v61, v62
	v_cndmask_b32_e64 v61, v61, v62, s[40:41]
	v_max_f32_e32 v61, v61, v61
	v_max_f32_e32 v60, v60, v61
	v_add_f32_e32 v61, 0x41000000, v161
	v_cmp_gt_f32_e32 vcc, v60, v61
	s_cbranch_vccz .LBB0_76
; __device__ __forceinline__ int crow(int r, int hi) { return (r & 3) + 8 * (r >> 2) + 4 * hi; }
; __device__ __forceinline__ float ex2(float x) { return __builtin_amdgcn_exp2f(x); }
; template <bool MASK> __device__ __forceinline__ void sm_tile(f32x16& p0, f32x16& p1, float& mrun, float& lrun, f32x16& o0, f32x16& o1, LAS float* wsf, int kv0, int qpos, int q32, int hi) {
;     ...
;     if (__any(rm > mrun + 8.0f)) {
;         const float mnew = fmaxf(mrun, rm), alpha = ex2(mrun - mnew); mrun = mnew; lrun *= alpha;
;         if (hi == 0) wsf[q32] = alpha;
;         __builtin_amdgcn_fence(__ATOMIC_RELEASE, "wavefront"); asm volatile("s_waitcnt lgkmcnt(0)" ::: "memory");
; #pragma unroll
;         for (int r = 0; r < 16; ++r) { const float al = wsf[crow(r, hi)]; o0[r] *= al; o1[r] *= al; }
	v_max_f32_e32 v60, v60, v60
	v_max_f32_e32 v61, v161, v161
	v_max_f32_e32 v171, v61, v60
	v_sub_f32_e32 v60, v161, v171
	v_exp_f32_e32 v60, v60
	s_and_saveexec_b64 s[18:19], s[40:41]
	ds_write_b32 v149, v60
	s_or_b64 exec, exec, s[18:19]
	s_waitcnt lgkmcnt(0)
	v_add_u32_e32 v161, s25, v148
	v_mul_f32_e32 v170, v170, v60
	ds_read_b128 v[60:63], v161
	ds_read_b128 v[72:75], v161 offset:32
	ds_read_b128 v[76:79], v161 offset:64
	ds_read_b128 v[178:181], v161 offset:96
	s_waitcnt lgkmcnt(3)
	v_pk_mul_f32 v[18:19], v[18:19], v[62:63]
	s_waitcnt lgkmcnt(2)
	v_pk_mul_f32 v[20:21], v[20:21], v[72:73]
	s_waitcnt lgkmcnt(1)
	v_pk_mul_f32 v[24:25], v[24:25], v[76:77]
	s_waitcnt lgkmcnt(0)
	v_pk_mul_f32 v[28:29], v[28:29], v[178:179]
	v_pk_mul_f32 v[30:31], v[30:31], v[180:181]
	v_pk_mul_f32 v[26:27], v[26:27], v[78:79]
	v_pk_mul_f32 v[22:23], v[22:23], v[74:75]
	v_pk_mul_f32 v[16:17], v[16:17], v[60:61]
	v_pk_mul_f32 v[44:45], v[44:45], v[178:179]
	v_pk_mul_f32 v[40:41], v[40:41], v[76:77]
	v_pk_mul_f32 v[36:37], v[36:37], v[72:73]
	v_pk_mul_f32 v[46:47], v[46:47], v[180:181]
	v_pk_mul_f32 v[42:43], v[42:43], v[78:79]
	v_pk_mul_f32 v[38:39], v[38:39], v[74:75]
	v_pk_mul_f32 v[34:35], v[34:35], v[62:63]
	v_pk_mul_f32 v[32:33], v[32:33], v[60:61]
	s_branch .LBB0_77

; #define LAS __attribute__((address_space(3)))
; __device__ __forceinline__ int crow(int r, int hi) { return (r & 3) + 8 * (r >> 2) + 4 * hi; }
; __device__ __forceinline__ float softplus2(float y) { return fmaxf(y, 0.f) + lg2(1.0f + ex2(-fabsf(y))); }
; #define MFMA32(a, b, c) __builtin_amdgcn_mfma_f32_32x32x16_bf16((a), (b), (c), 0, 0, 0)
; template <bool MASK> __device__ __forceinline__ void sb_tile(f32x16& p0, f32x16& p1, float& carry, int kv0, int qpos, int hi) {
;     ...
;     for (int r = 0; r < 16; ++r) { float s0 = softplus2(p0[r]), s1 = softplus2(p1[r]);
;         if (MASK) { if (kv0 + crow(r, hi) >= qpos) s0 = 0.f; if (kv0 + 32 + crow(r, hi) >= qpos) s1 = 0.f; }
;         sp0[r] = s0; sp1[r] = s1; }
; __device__ __forceinline__ void attn_unit_sb(int b, int h, int qb, const bf16_t* __restrict__ Q, const bf16_t* __restrict__ K, const bf16_t* __restrict__ Vt, bf16_t* __restrict__ O, LAS unsigned char* lds) {
;     ...
; #pragma unroll
;             for (int d0 = 0; d0 < ND; ++d0) { const bf16x8 a0 = *(const LAS bf16x8*)(kb + d0 * 32), a1 = *(const LAS bf16x8*)(kb + 32 * KP + d0 * 32);
;                 p0 = MFMA32(a0, qr[d0], p0); p1 = MFMA32(a1, qr[d0], p1); }
;             sb_tile<true>(p0, p1, carry, jt * 64, qpos, hi);
.LBB0_489:
	v_add_u32_e32 v14, 0, v198
	ds_read_b128 v[2:5], v14 offset:4608
	ds_read_b128 v[6:9], v14
	ds_read_b128 v[10:13], v14 offset:32
	s_add_i32 s5, s19, 32
	v_or_b32_e32 v197, s19, v101
	s_waitcnt lgkmcnt(2)
	v_mfma_f32_32x32x16_bf16 v[64:79], v[2:5], v[84:87], 0
	ds_read_b128 v[2:5], v14 offset:4640
	v_or_b32_e32 v199, s5, v108
	v_cmp_lt_i32_e64 s[58:59], v199, v104
	v_cmp_lt_i32_e64 s[6:7], v197, v105
	v_or_b32_e32 v197, s19, v109
	v_or_b32_e32 v199, s5, v110
	v_cmp_lt_i32_e64 s[60:61], v199, v104
	s_waitcnt lgkmcnt(2)
	v_mfma_f32_32x32x16_bf16 v[48:63], v[6:9], v[84:87], 0
	v_cmp_lt_i32_e64 s[44:45], v197, v105
	v_or_b32_e32 v197, s19, v111
	v_or_b32_e32 v199, s5, v112
	v_cmp_lt_i32_e64 s[62:63], v199, v104
	v_cmp_lt_i32_e64 s[46:47], v197, v105
	v_or_b32_e32 v197, s19, v113
	v_or_b32_e32 v199, s5, v114
	s_waitcnt lgkmcnt(1)
	v_mfma_f32_32x32x16_bf16 v[48:63], v[10:13], v[88:91], v[48:63]
	v_cmp_lt_i32_e64 s[64:65], v199, v104
	v_cmp_lt_i32_e64 s[48:49], v197, v105
	v_or_b32_e32 v197, s19, v115
	v_or_b32_e32 v199, s5, v116
	v_cmp_lt_i32_e64 s[66:67], v199, v104
	v_cmp_lt_i32_e64 s[50:51], v197, v105
	v_or_b32_e32 v197, s19, v117
	s_waitcnt lgkmcnt(0)
	v_mfma_f32_32x32x16_bf16 v[64:79], v[2:5], v[88:91], v[64:79]
	ds_read_b128 v[2:5], v14 offset:64
	ds_read_b128 v[6:9], v14 offset:4672
	v_or_b32_e32 v199, s5, v118
	v_cmp_lt_i32_e64 s[68:69], v199, v104
	v_cmp_lt_i32_e64 s[52:53], v197, v105
	v_or_b32_e32 v197, s19, v119
	v_or_b32_e32 v199, s5, v120
	v_cmp_lt_i32_e64 s[70:71], v199, v104
	s_waitcnt lgkmcnt(1)
	v_mfma_f32_32x32x16_bf16 v[48:63], v[2:5], v[92:95], v[48:63]
	v_cmp_lt_i32_e64 s[54:55], v197, v105
	v_or_b32_e32 v197, s19, v121
	v_or_b32_e32 v199, s5, v122
	v_cmp_lt_i32_e64 s[72:73], v199, v104
	v_cmp_lt_i32_e64 s[56:57], v197, v105
	v_or_b32_e32 v197, s19, v123
	v_or_b32_e32 v199, s5, v124
	s_waitcnt lgkmcnt(0)
	v_mfma_f32_32x32x16_bf16 v[64:79], v[6:9], v[92:95], v[64:79]
	ds_read_b128 v[2:5], v14 offset:96
	ds_read_b128 v[6:9], v14 offset:4704
	v_cmp_lt_i32_e64 s[74:75], v199, v104
	v_cmp_lt_i32_e64 s[76:77], v197, v105
	v_or_b32_e32 v197, s19, v125
	v_or_b32_e32 v199, s5, v126
	v_cmp_lt_i32_e64 s[78:79], v199, v104
	v_cmp_lt_i32_e64 s[80:81], v197, v105
	s_waitcnt lgkmcnt(1)
	v_mfma_f32_32x32x16_bf16 v[48:63], v[2:5], v[96:99], v[48:63]
	v_or_b32_e32 v197, s19, v127
	v_or_b32_e32 v199, s5, v128
	v_cmp_lt_i32_e64 s[82:83], v199, v104
	v_cmp_lt_i32_e64 s[84:85], v197, v105
	v_or_b32_e32 v197, s19, v129
	v_or_b32_e32 v199, s5, v130
	v_cmp_lt_i32_e64 s[86:87], v199, v104
	s_waitcnt lgkmcnt(0)
	v_mfma_f32_32x32x16_bf16 v[64:79], v[6:9], v[96:99], v[64:79]
	s_nop 2
	v_exp_f32_e64 v5, -|v49|
	v_exp_f32_e64 v2, -|v48|
	v_max_f32_e32 v9, v49, v49
	v_max_f32_e32 v9, 0, v9
	v_add_f32_e32 v5, 1.0, v5
	v_log_f32_e32 v7, v5
	v_add_f32_e32 v2, 1.0, v2
	s_nop 1
	v_max_f32_e32 v5, v65, v65
	v_max_f32_e32 v8, 0, v5
	v_exp_f32_e64 v5, -|v65|
	v_log_f32_e32 v3, v2
	v_max_f32_e32 v2, v64, v64
	v_max_f32_e32 v4, 0, v2
	v_add_f32_e32 v5, 1.0, v5
	v_log_f32_e32 v6, v5
	v_exp_f32_e64 v5, -|v50|
	v_exp_f32_e64 v2, -|v64|
	v_max_f32_e32 v13, v50, v50
	v_max_f32_e32 v13, 0, v13
	v_add_f32_e32 v5, 1.0, v5
	v_log_f32_e32 v11, v5
	v_max_f32_e32 v12, 0, v66
	v_exp_f32_e64 v5, -|v66|
	v_add_f32_e32 v2, 1.0, v2
	v_log_f32_e32 v2, v2
	v_max_f32_e32 v141, v51, v51
	v_add_f32_e32 v5, 1.0, v5
	v_log_f32_e32 v10, v5
	v_exp_f32_e64 v5, -|v51|
	v_max_f32_e32 v141, 0, v141
	v_add_f32_e32 v5, 1.0, v5
	v_log_f32_e32 v15, v5
	v_max_f32_e32 v140, 0, v67
	v_exp_f32_e64 v5, -|v67|
	v_max_f32_e32 v145, 0, v52
	v_max_f32_e32 v161, 0, v56
	v_add_f32_e32 v5, 1.0, v5
	v_log_f32_e32 v14, v5
	v_exp_f32_e64 v5, -|v52|
	v_max_f32_e32 v165, v57, v57
	v_max_f32_e32 v149, 0, v53
	v_max_f32_e32 v165, 0, v165
	v_add_f32_e32 v5, 1.0, v5
	v_log_f32_e32 v143, v5
	v_max_f32_e32 v144, 0, v68
	v_exp_f32_e64 v5, -|v68|
	v_max_f32_e32 v169, v58, v58
	v_max_f32_e32 v169, 0, v169
	v_add_f32_e32 v5, 1.0, v5
	v_log_f32_e32 v142, v5
	v_exp_f32_e64 v5, -|v53|
	v_max_f32_e32 v173, v59, v59
	v_max_f32_e32 v153, 0, v54
	v_max_f32_e32 v173, 0, v173
	v_add_f32_e32 v5, 1.0, v5
	v_log_f32_e32 v147, v5
	v_max_f32_e32 v148, 0, v69
	v_exp_f32_e64 v5, -|v69|
	v_max_f32_e32 v177, v60, v60
	v_max_f32_e32 v177, 0, v177
	v_add_f32_e32 v5, 1.0, v5
	v_log_f32_e32 v146, v5
	v_exp_f32_e64 v5, -|v54|
	v_max_f32_e32 v181, v61, v61
	v_cmp_lt_i32_e64 s[88:89], v197, v105
	v_or_b32_e32 v197, s19, v131
	v_add_f32_e32 v5, 1.0, v5
	v_log_f32_e32 v151, v5
	v_max_f32_e32 v152, 0, v70
	v_exp_f32_e64 v5, -|v70|
	v_or_b32_e32 v199, s5, v132
	v_max_f32_e32 v157, 0, v55
	v_max_f32_e32 v181, 0, v181
	v_add_f32_e32 v5, 1.0, v5
	v_log_f32_e32 v150, v5
	v_exp_f32_e64 v5, -|v55|
	v_max_f32_e32 v185, v62, v62
	v_cmp_lt_i32_e64 s[90:91], v199, v104
	v_cmp_lt_i32_e64 s[92:93], v197, v105
	v_add_f32_e32 v5, 1.0, v5
	v_log_f32_e32 v155, v5
	v_max_f32_e32 v156, 0, v71
	v_exp_f32_e64 v5, -|v71|
	v_or_b32_e32 v197, s19, v133
	v_or_b32_e32 v199, s5, v134
	v_max_f32_e32 v185, 0, v185
	v_add_f32_e32 v5, 1.0, v5
	v_log_f32_e32 v154, v5
	v_exp_f32_e64 v5, -|v56|
	v_max_f32_e32 v189, v63, v63
	v_cmp_lt_i32_e64 s[94:95], v199, v104
	v_cmp_lt_i32_e64 s[96:97], v197, v105
	v_add_f32_e32 v5, 1.0, v5
	v_log_f32_e32 v159, v5
	v_max_f32_e32 v160, 0, v72
	v_exp_f32_e64 v5, -|v72|
	v_or_b32_e32 v197, s19, v135
	v_or_b32_e32 v199, s5, v136
	s_mov_b32 s4, s10
	v_add_f32_e32 v5, 1.0, v5
	v_log_f32_e32 v158, v5
	v_exp_f32_e64 v5, -|v57|
	v_max_f32_e32 v189, 0, v189
	v_cmp_lt_i32_e64 s[8:9], v199, v104
	v_cmp_lt_i32_e64 s[10:11], v197, v105
	v_add_f32_e32 v5, 1.0, v5
	v_log_f32_e32 v163, v5
	v_max_f32_e32 v164, 0, v73
	v_exp_f32_e64 v5, -|v73|
; __device__ __forceinline__ int crow(int r, int hi) { return (r & 3) + 8 * (r >> 2) + 4 * hi; }
; __device__ __forceinline__ float softplus2(float y) { return fmaxf(y, 0.f) + lg2(1.0f + ex2(-fabsf(y))); }
; template <bool MASK> __device__ __forceinline__ void sb_tile(f32x16& p0, f32x16& p1, float& carry, int kv0, int qpos, int hi) {
;     ...
;     for (int r = 0; r < 16; ++r) { float s0 = softplus2(p0[r]), s1 = softplus2(p1[r]);
;         if (MASK) { if (kv0 + crow(r, hi) >= qpos) s0 = 0.f; if (kv0 + 32 + crow(r, hi) >= qpos) s1 = 0.f; }
;         sp0[r] = s0; sp1[r] = s1; }
;     float tl0[4], tl1[4], bt0, bt1;
;     { float G[4], Go[4], T[4];
; #pragma unroll
;       for (int i = 0; i < 4; ++i) { sp1[4 * i + 2] += sp1[4 * i + 3]; sp1[4 * i + 1] += sp1[4 * i + 2]; sp1[4 * i] += sp1[4 * i + 1]; G[i] = sp1[4 * i]; }
; #pragma unroll
;       for (int i = 0; i < 4; ++i) { Go[i] = xhalf(G[i], hi); T[i] = G[i] + Go[i]; }
;       const float st2 = T[3], st1 = T[3] + T[2], st0 = st1 + T[1]; bt1 = st0 + T[0];
;       tl1[3] = carry + (hi ? 0.f : Go[3]); tl1[2] = carry + st2 + (hi ? 0.f : Go[2]); tl1[1] = carry + st1 + (hi ? 0.f : Go[1]); tl1[0] = carry + st0 + (hi ? 0.f : Go[0]); }
;     { float G[4], Go[4], T[4]; const float base = carry + bt1;
; #pragma unroll
;       for (int i = 0; i < 4; ++i) { sp0[4 * i + 2] += sp0[4 * i + 3]; sp0[4 * i + 1] += sp0[4 * i + 2]; sp0[4 * i] += sp0[4 * i + 1]; G[i] = sp0[4 * i]; }
; #pragma unroll
;       for (int i = 0; i < 4; ++i) { Go[i] = xhalf(G[i], hi); T[i] = G[i] + Go[i]; }
;       const float st2 = T[3], st1 = T[3] + T[2], st0 = st1 + T[1]; bt0 = st0 + T[0];
;       tl0[3] = base + (hi ? 0.f : Go[3]); tl0[2] = base + st2 + (hi ? 0.f : Go[2]); tl0[1] = base + st1 + (hi ? 0.f : Go[1]); tl0[0] = base + st0 + (hi ? 0.f : Go[0]); }
	v_or_b32_e32 v197, s19, v137
	v_or_b32_e32 v199, s5, v138
	v_cmp_lt_i32_e64 s[12:13], v199, v104
	v_add_f32_e32 v5, 1.0, v5
	v_log_f32_e32 v162, v5
	v_exp_f32_e64 v5, -|v58|
	v_cmp_lt_i32_e32 vcc, v197, v105
	s_mov_b32 s5, 0x43200000
	v_add_u32_e32 v198, 0xffffdc00, v198
	v_add_f32_e32 v5, 1.0, v5
	v_log_f32_e32 v167, v5
	v_max_f32_e32 v168, 0, v74
	v_exp_f32_e64 v5, -|v74|
	s_nop 0
	v_add_f32_e32 v5, 1.0, v5
	v_log_f32_e32 v166, v5
	v_exp_f32_e64 v5, -|v59|
	s_nop 0
	v_add_f32_e32 v5, 1.0, v5
	v_log_f32_e32 v171, v5
	v_max_f32_e32 v172, 0, v75
	v_exp_f32_e64 v5, -|v75|
	s_nop 0
	v_add_f32_e32 v5, 1.0, v5
	v_log_f32_e32 v170, v5
	v_exp_f32_e64 v5, -|v60|
	s_nop 0
	v_add_f32_e32 v5, 1.0, v5
	v_log_f32_e32 v175, v5
	v_max_f32_e32 v176, 0, v76
	v_exp_f32_e64 v5, -|v76|
	s_nop 0
	v_add_f32_e32 v5, 1.0, v5
	v_log_f32_e32 v174, v5
	v_exp_f32_e64 v5, -|v61|
	s_nop 0
	v_add_f32_e32 v5, 1.0, v5
	v_log_f32_e32 v179, v5
	v_max_f32_e32 v180, 0, v77
	v_exp_f32_e64 v5, -|v77|
	s_nop 0
	v_add_f32_e32 v5, 1.0, v5
	v_log_f32_e32 v178, v5
	v_exp_f32_e64 v5, -|v62|
	s_nop 0
	v_add_f32_e32 v5, 1.0, v5
	v_log_f32_e32 v183, v5
	v_max_f32_e32 v184, 0, v78
	v_exp_f32_e64 v5, -|v78|
	s_nop 0
	v_add_f32_e32 v5, 1.0, v5
	v_log_f32_e32 v182, v5
	v_exp_f32_e64 v5, -|v63|
	s_nop 0
	v_add_f32_e32 v5, 1.0, v5
	v_log_f32_e32 v187, v5
	v_max_f32_e32 v188, 0, v79
	v_exp_f32_e64 v5, -|v79|
	s_nop 0
	v_add_f32_e32 v5, 1.0, v5
	v_log_f32_e32 v186, v5
	v_max_f32_e32 v5, 0, v48
	v_pk_add_f32 v[2:3], v[4:5], v[2:3]
	s_nop 0
	v_cndmask_b32_e64 v201, 0, v3, s[6:7]
	v_cndmask_b32_e64 v200, 0, v2, s[58:59]
	v_pk_add_f32 v[2:3], v[8:9], v[6:7]
	s_nop 0
	v_cndmask_b32_e64 v7, 0, v3, s[44:45]
	v_cndmask_b32_e64 v6, 0, v2, s[60:61]
	v_pk_add_f32 v[2:3], v[12:13], v[10:11]
	v_pk_add_f32 v[12:13], v[160:161], v[158:159]
	v_cndmask_b32_e64 v9, 0, v3, s[46:47]
	v_cndmask_b32_e64 v8, 0, v2, s[62:63]
	v_pk_add_f32 v[2:3], v[140:141], v[14:15]
	s_nop 0
	v_cndmask_b32_e64 v5, 0, v3, s[48:49]
	v_cndmask_b32_e64 v4, 0, v2, s[64:65]
	v_pk_add_f32 v[2:3], v[144:145], v[142:143]
	s_nop 0
	v_cndmask_b32_e64 v11, 0, v3, s[50:51]
	v_cndmask_b32_e64 v10, 0, v2, s[66:67]
	v_pk_add_f32 v[2:3], v[148:149], v[146:147]
	v_cndmask_b32_e64 v147, 0, v13, s[76:77]
	v_cndmask_b32_e64 v146, 0, v12, s[74:75]
	v_pk_add_f32 v[12:13], v[164:165], v[162:163]
	v_cndmask_b32_e64 v143, 0, v3, s[52:53]
	v_cndmask_b32_e64 v149, 0, v13, s[80:81]
	v_cndmask_b32_e64 v148, 0, v12, s[78:79]
	v_pk_add_f32 v[12:13], v[168:169], v[166:167]
	v_cndmask_b32_e64 v142, 0, v2, s[68:69]
	v_pk_add_f32 v[2:3], v[152:153], v[150:151]
	v_cndmask_b32_e64 v151, 0, v13, s[84:85]
	v_cndmask_b32_e64 v150, 0, v12, s[82:83]
	v_pk_add_f32 v[12:13], v[172:173], v[170:171]
	v_cndmask_b32_e64 v145, 0, v3, s[54:55]
	v_cndmask_b32_e64 v153, 0, v13, s[88:89]
	v_cndmask_b32_e64 v152, 0, v12, s[86:87]
	v_pk_add_f32 v[12:13], v[176:177], v[174:175]
	v_cndmask_b32_e64 v144, 0, v2, s[70:71]
	v_pk_add_f32 v[2:3], v[156:157], v[154:155]
	v_cndmask_b32_e64 v155, 0, v13, s[92:93]
	v_cndmask_b32_e64 v154, 0, v12, s[90:91]
	v_pk_add_f32 v[12:13], v[180:181], v[178:179]
	v_pk_add_f32 v[150:151], v[150:151], v[152:153]
	v_cndmask_b32_e64 v157, 0, v13, s[96:97]
	v_cndmask_b32_e64 v156, 0, v12, s[94:95]
	v_pk_add_f32 v[12:13], v[184:185], v[182:183]
	v_cndmask_b32_e64 v3, 0, v3, s[56:57]
	v_cndmask_b32_e64 v159, 0, v13, s[10:11]
	v_cndmask_b32_e64 v158, 0, v12, s[8:9]
	v_pk_add_f32 v[12:13], v[188:189], v[186:187]
	v_cndmask_b32_e64 v2, 0, v2, s[72:73]
	v_cndmask_b32_e32 v161, 0, v13, vcc
	v_cndmask_b32_e64 v160, 0, v12, s[12:13]
	v_pk_add_f32 v[158:159], v[158:159], v[160:161]
	v_pk_add_f32 v[12:13], v[8:9], v[4:5]
	v_pk_add_f32 v[156:157], v[156:157], v[158:159]
	v_pk_add_f32 v[162:163], v[148:149], v[150:151]
	v_pk_add_f32 v[154:155], v[154:155], v[156:157]
	v_pk_add_f32 v[14:15], v[6:7], v[12:13]
	v_pk_add_f32 v[6:7], v[144:145], v[2:3]
	v_pk_add_f32 v[164:165], v[146:147], v[162:163]
	v_mov_b32_e32 v145, v154
	v_mov_b32_e32 v146, v154
	v_mov_b32_e32 v147, v155
	v_mov_b32_e32 v148, v155
	v_pk_add_f32 v[8:9], v[142:143], v[6:7]
	v_mov_b32_e32 v142, v164
	v_mov_b32_e32 v143, v164
	v_permlane32_swap_b32_e32 v145, v146
	v_permlane32_swap_b32_e32 v147, v148
	v_permlane32_swap_b32_e32 v142, v143
	v_cndmask_b32_e64 v167, v147, v148, s[40:41]
	v_cndmask_b32_e64 v166, v145, v146, s[40:41]
	v_mov_b32_e32 v146, v165
	v_mov_b32_e32 v147, v165
	v_pk_add_f32 v[10:11], v[10:11], v[8:9]
	v_cndmask_b32_e64 v145, 0, v166, s[40:41]
	v_pk_add_f32 v[168:169], v[154:155], v[166:167]
	v_permlane32_swap_b32_e32 v146, v147
	v_cndmask_b32_e64 v170, v142, v143, s[40:41]
	v_mov_b32_e32 v144, v10
	v_mov_b32_e32 v174, v10
	v_add_f32_e32 v175, v195, v145
	v_add_f32_e32 v145, v195, v168
	v_cndmask_b32_e64 v171, v146, v147, s[40:41]
	v_cndmask_b32_e64 v142, 0, v170, s[40:41]
	v_permlane32_swap_b32_e32 v144, v174
	v_add_f32_e32 v166, v142, v145
	v_pk_add_f32 v[142:143], v[164:165], v[170:171]
	v_mov_b32_e32 v145, v11
	v_mov_b32_e32 v147, v11
	v_pk_add_f32 v[142:143], v[142:143], v[168:169]
	s_nop 0
	v_permlane32_swap_b32_e32 v145, v147
	v_cndmask_b32_e64 v144, v144, v174, s[40:41]
	v_pk_add_f32 v[140:141], v[200:201], v[14:15]
	v_add_f32_e32 v146, v195, v142
	v_cndmask_b32_e64 v145, v145, v147, s[40:41]
	v_cndmask_b32_e64 v147, 0, v144, s[40:41]
	v_mov_b32_e32 v172, v140
	v_mov_b32_e32 v173, v140
	v_add_f32_e32 v168, v147, v146
	v_pk_add_f32 v[146:147], v[10:11], v[144:145]
	v_mov_b32_e32 v144, v141
	v_mov_b32_e32 v148, v141
	v_permlane32_swap_b32_e32 v172, v173
	s_nop 0
	v_permlane32_swap_b32_e32 v144, v148
	v_cndmask_b32_e64 v149, v144, v148, s[40:41]
	v_cndmask_b32_e64 v148, v172, v173, s[40:41]
; #define LAS __attribute__((address_space(3)))
; __device__ __forceinline__ unsigned pk2(float lo, float hi) { f32x2_t v = {lo, hi}; bf16x2_t b = __builtin_convertvector(v, bf16x2_t); return __builtin_bit_cast(unsigned, b); }
; template <bool MASK> __device__ __forceinline__ void sb_tile(f32x16& p0, f32x16& p1, float& carry, int kv0, int qpos, int hi) {
;     ...
;       const float st2 = T[3], st1 = T[3] + T[2], st0 = st1 + T[1]; bt0 = st0 + T[0];
;       tl0[3] = base + (hi ? 0.f : Go[3]); tl0[2] = base + st2 + (hi ? 0.f : Go[2]); tl0[1] = base + st1 + (hi ? 0.f : Go[1]); tl0[0] = base + st0 + (hi ? 0.f : Go[0]); }
;     carry += bt0 + bt1;
; #pragma unroll
;     for (int r = 0; r < 16; ++r) { float w0 = ex2(p0[r] - (sp0[r] + tl0[r >> 2])), w1 = ex2(p1[r] - (sp1[r] + tl1[r >> 2]));
;         if (MASK) { if (kv0 + crow(r, hi) >= qpos) w0 = 0.f; if (kv0 + 32 + crow(r, hi) >= qpos) w1 = 0.f; }
;         p0[r] = w0; p1[r] = w1; }
; __device__ __forceinline__ void attn_unit_sb(int b, int h, int qb, const bf16_t* __restrict__ Q, const bf16_t* __restrict__ K, const bf16_t* __restrict__ Vt, bf16_t* __restrict__ O, LAS unsigned char* lds) {
;     ...
;             const LAS unsigned char* vb = lds + OFF_V + s * VBUF + q32 * VP + hi * 8;
; #pragma unroll
;             for (int j = 0; j < 4; ++j) {
;                 u32x4 pw;
;                 if (j < 2) { const int r0 = 8 * (j & 1); pw.x = pk2(p0[r0], p0[r0 + 1]); pw.y = pk2(p0[r0 + 2], p0[r0 + 3]); pw.z = pk2(p0[r0 + 4], p0[r0 + 5]); pw.w = pk2(p0[r0 + 6], p0[r0 + 7]); }
;                 else { const int r0 = 8 * (j & 1); pw.x = pk2(p1[r0], p1[r0 + 1]); pw.y = pk2(p1[r0 + 2], p1[r0 + 3]); pw.z = pk2(p1[r0 + 4], p1[r0 + 5]); pw.w = pk2(p1[r0 + 6], p1[r0 + 7]); }
;                 const bf16x8 pa = __builtin_bit_cast(bf16x8, pw);
;                 { const s16x4 l4 = *(const LAS s16x4*)(vb + j * 32), hh = *(const LAS s16x4*)(vb + j * 32 + 16);
;                   const bf16x8 vf = {l4[0], l4[1], l4[2], l4[3], hh[0], hh[1], hh[2], hh[3]}; o0 = MFMA32(pa, vf, o0); }
;                 { const s16x4 l4 = *(const LAS s16x4*)(vb + 32 * VP + j * 32), hh = *(const LAS s16x4*)(vb + 32 * VP + j * 32 + 16);
;                   const bf16x8 vf = {l4[0], l4[1], l4[2], l4[3], hh[0], hh[1], hh[2], hh[3]}; o1 = MFMA32(pa, vf, o1); }
;             }
;             done = __all(carry > SB_DONE);
	v_pk_add_f32 v[146:147], v[146:147], v[142:143]
	v_pk_add_f32 v[172:173], v[140:141], v[148:149]
	v_add_f32_e32 v142, v195, v146
	v_cndmask_b32_e64 v144, 0, v148, s[40:41]
	v_pk_add_f32 v[172:173], v[172:173], v[146:147]
	v_add_f32_e32 v170, v144, v142
	v_add_f32_e32 v144, v195, v172
	v_cndmask_b32_e64 v142, 0, v167, s[40:41]
	v_add_f32_e32 v146, v142, v144
	v_add_f32_e32 v142, v169, v144
	v_cndmask_b32_e64 v148, 0, v171, s[40:41]
	v_add_f32_e32 v148, v148, v142
	v_add_f32_e32 v14, v14, v170
	v_sub_f32_e32 v14, v65, v14
	v_add_f32_e32 v65, v165, v148
	v_sub_f32_e32 v56, v56, v65
	v_add_f32_e32 v65, v164, v166
	v_add_f32_e32 v12, v12, v170
	v_sub_f32_e32 v65, v72, v65
	v_sub_f32_e32 v12, v66, v12
	v_exp_f32_e32 v56, v56
	v_exp_f32_e32 v66, v65
	v_add_f32_e32 v4, v4, v170
	v_sub_f32_e32 v4, v67, v4
	v_cndmask_b32_e64 v65, 0, v56, s[76:77]
	v_cndmask_b32_e64 v56, 0, v66, s[74:75]
	v_add_f32_e32 v66, v163, v148
	v_sub_f32_e32 v57, v57, v66
	v_add_f32_e32 v66, v162, v166
	v_sub_f32_e32 v66, v73, v66
	v_exp_f32_e32 v57, v57
	v_exp_f32_e32 v67, v66
	v_add_f32_e32 v10, v10, v168
	v_sub_f32_e32 v10, v68, v10
	v_cndmask_b32_e64 v66, 0, v57, s[80:81]
	v_cndmask_b32_e64 v57, 0, v67, s[78:79]
	v_add_f32_e32 v67, v151, v148
	v_sub_f32_e32 v58, v58, v67
	v_add_f32_e32 v67, v150, v166
	v_sub_f32_e32 v67, v74, v67
	v_exp_f32_e32 v58, v58
	v_exp_f32_e32 v68, v67
	v_add_f32_e32 v8, v8, v168
	v_sub_f32_e32 v8, v69, v8
	v_cndmask_b32_e64 v67, 0, v58, s[84:85]
	v_cndmask_b32_e64 v58, 0, v68, s[82:83]
	v_add_f32_e32 v68, v153, v148
	v_sub_f32_e32 v59, v59, v68
	v_add_f32_e32 v68, v152, v166
	v_sub_f32_e32 v68, v75, v68
	v_exp_f32_e32 v59, v59
	v_exp_f32_e32 v69, v68
	v_add_f32_e32 v6, v6, v168
	v_sub_f32_e32 v6, v70, v6
	v_cndmask_b32_e64 v68, 0, v59, s[88:89]
	v_cndmask_b32_e64 v59, 0, v69, s[86:87]
	v_add_f32_e32 v69, v155, v146
	v_sub_f32_e32 v60, v60, v69
	v_add_f32_e32 v69, v175, v154
	v_sub_f32_e32 v69, v76, v69
	v_exp_f32_e32 v60, v60
	v_exp_f32_e32 v70, v69
	v_add_f32_e32 v2, v2, v168
	v_sub_f32_e32 v2, v71, v2
	v_cndmask_b32_e64 v69, 0, v60, s[92:93]
	v_cndmask_b32_e64 v60, 0, v70, s[90:91]
	v_add_f32_e32 v70, v157, v146
	v_sub_f32_e32 v61, v61, v70
	v_add_f32_e32 v70, v156, v175
	v_sub_f32_e32 v70, v77, v70
	v_exp_f32_e32 v61, v61
	v_exp_f32_e32 v71, v70
	v_cndmask_b32_e64 v74, 0, v149, s[40:41]
	v_add_f32_e32 v75, v147, v144
	v_add_f32_e32 v74, v74, v75
	v_add_f32_e32 v13, v13, v74
	v_add_f32_e32 v5, v5, v74
	v_cndmask_b32_e64 v70, 0, v61, s[96:97]
	v_cndmask_b32_e64 v61, 0, v71, s[94:95]
	v_add_f32_e32 v71, v159, v146
	v_sub_f32_e32 v13, v50, v13
	v_sub_f32_e32 v5, v51, v5
	v_sub_f32_e32 v62, v62, v71
	v_add_f32_e32 v71, v158, v175
	v_exp_f32_e32 v13, v13
	v_exp_f32_e32 v5, v5
	v_sub_f32_e32 v71, v78, v71
	v_exp_f32_e32 v62, v62
	v_exp_f32_e32 v72, v71
	v_add_f32_e32 v15, v15, v74
	v_cndmask_b32_e64 v13, 0, v13, s[46:47]
	v_cndmask_b32_e64 v5, 0, v5, s[48:49]
	v_sub_f32_e32 v15, v49, v15
	v_cvt_pk_bf16_f32 v49, v13, v5
	v_cndmask_b32_e64 v5, 0, v145, s[40:41]
	v_add_f32_e32 v13, v143, v144
	v_cndmask_b32_e64 v71, 0, v62, s[10:11]
	v_cndmask_b32_e64 v62, 0, v72, s[8:9]
	v_add_f32_e32 v72, v161, v146
	v_add_f32_e32 v5, v5, v13
	v_sub_f32_e32 v63, v63, v72
	v_add_f32_e32 v72, v160, v175
	v_add_f32_e32 v75, v141, v74
	v_add_f32_e32 v11, v11, v5
	v_add_f32_e32 v9, v9, v5
	v_add_f32_e32 v7, v7, v5
	v_add_f32_e32 v3, v3, v5
	v_sub_f32_e32 v72, v79, v72
	v_sub_f32_e32 v48, v48, v75
	v_sub_f32_e32 v11, v52, v11
	v_sub_f32_e32 v9, v53, v9
	v_sub_f32_e32 v7, v54, v7
	v_sub_f32_e32 v3, v55, v3
	v_exp_f32_e32 v63, v63
	v_exp_f32_e32 v73, v72
	v_exp_f32_e32 v48, v48
	v_exp_f32_e32 v15, v15
	v_exp_f32_e32 v11, v11
	v_exp_f32_e32 v9, v9
	v_exp_f32_e32 v7, v7
	v_exp_f32_e32 v3, v3
	v_cndmask_b32_e32 v72, 0, v63, vcc
	v_cndmask_b32_e64 v63, 0, v73, s[12:13]
	v_add_u32_e32 v73, 0, v1
	v_cndmask_b32_e64 v48, 0, v48, s[6:7]
	v_cndmask_b32_e64 v15, 0, v15, s[44:45]
	v_cndmask_b32_e64 v11, 0, v11, s[50:51]
	v_cndmask_b32_e64 v9, 0, v9, s[52:53]
	v_cndmask_b32_e64 v7, 0, v7, s[54:55]
	v_cndmask_b32_e64 v3, 0, v3, s[56:57]
	v_cvt_pk_bf16_f32 v48, v48, v15
	v_cvt_pk_bf16_f32 v50, v11, v9
	v_cvt_pk_bf16_f32 v51, v7, v3
	v_add_u32_e32 v7, 0xf800, v73
	ds_read2_b64 v[52:55], v7 offset0:128 offset1:130
	ds_read2_b64 v[74:77], v7 offset0:132 offset1:134
	v_add_u32_e32 v78, 0x10d00, v73
	v_add_u32_e32 v3, 0x10d10, v73
	s_waitcnt lgkmcnt(1)
	v_mfma_f32_32x32x16_bf16 v[16:31], v[48:51], v[52:55], v[16:31]
	ds_read_b64 v[52:53], v78
	ds_read_b64 v[54:55], v3
	v_add_f32_e32 v140, v140, v170
	v_add_u32_e32 v3, 0x10d20, v73
	v_sub_f32_e32 v64, v64, v140
	v_exp_f32_e32 v64, v64
	v_exp_f32_e32 v14, v14
	s_waitcnt lgkmcnt(0)
	v_mfma_f32_32x32x16_bf16 v[32:47], v[48:51], v[52:55], v[32:47]
	v_cvt_pk_bf16_f32 v48, v65, v66
	v_cvt_pk_bf16_f32 v49, v67, v68
	v_cvt_pk_bf16_f32 v50, v69, v70
	v_cvt_pk_bf16_f32 v51, v71, v72
	ds_read_b64 v[52:53], v3
	v_add_u32_e32 v3, 0x10d30, v73
	v_exp_f32_e32 v12, v12
	v_exp_f32_e32 v4, v4
	v_exp_f32_e32 v10, v10
	v_exp_f32_e32 v8, v8
	v_exp_f32_e32 v6, v6
	v_exp_f32_e32 v2, v2
	ds_read_b64 v[54:55], v3
	v_mfma_f32_32x32x16_bf16 v[16:31], v[48:51], v[74:77], v[16:31]
	v_cndmask_b32_e64 v64, 0, v64, s[58:59]
	v_cndmask_b32_e64 v14, 0, v14, s[60:61]
	v_cndmask_b32_e64 v12, 0, v12, s[62:63]
	v_cndmask_b32_e64 v4, 0, v4, s[64:65]
	v_cndmask_b32_e64 v10, 0, v10, s[66:67]
	v_cndmask_b32_e64 v8, 0, v8, s[68:69]
	v_cndmask_b32_e64 v6, 0, v6, s[70:71]
	v_cndmask_b32_e64 v2, 0, v2, s[72:73]
	s_waitcnt lgkmcnt(0)
	v_mfma_f32_32x32x16_bf16 v[32:47], v[48:51], v[52:55], v[32:47]
	v_cvt_pk_bf16_f32 v48, v64, v14
	v_cvt_pk_bf16_f32 v49, v12, v4
	v_cvt_pk_bf16_f32 v50, v10, v8
	v_cvt_pk_bf16_f32 v51, v6, v2
	ds_read2_b64 v[2:5], v7 offset0:136 offset1:138
	ds_read2_b64 v[6:9], v7 offset0:140 offset1:142
	v_add_f32_e32 v142, v172, v173
	s_waitcnt lgkmcnt(1)
	v_mfma_f32_32x32x16_bf16 v[16:31], v[48:51], v[2:5], v[16:31]
	v_add_u32_e32 v2, 0x10d40, v73
	v_add_u32_e32 v4, 0x10d50, v73
	ds_read_b64 v[2:3], v2
	ds_read_b64 v[4:5], v4
	v_add_f32_e32 v195, v195, v142
	v_cmp_lt_f32_e32 vcc, s5, v195
	s_cmp_eq_u64 vcc, exec
	s_waitcnt lgkmcnt(0)
	v_mfma_f32_32x32x16_bf16 v[32:47], v[48:51], v[2:5], v[32:47]
	v_cvt_pk_bf16_f32 v2, v56, v57
	v_cvt_pk_bf16_f32 v3, v58, v59
	v_cvt_pk_bf16_f32 v4, v60, v61
	v_cvt_pk_bf16_f32 v5, v62, v63
	s_cselect_b64 s[6:7], -1, 0
	s_add_i32 s10, s4, -1
	s_cmp_le_u32 s4, s0
	v_mfma_f32_32x32x16_bf16 v[16:31], v[2:5], v[6:9], v[16:31]
	v_add_u32_e32 v6, 0x10d60, v73
	v_add_u32_e32 v8, 0x10d70, v73
	ds_read_b64 v[6:7], v6
	ds_read_b64 v[8:9], v8
	s_cselect_b64 s[4:5], -1, 0
	s_or_b64 s[8:9], s[4:5], s[6:7]
	s_sub_i32 s19, s19, 64
	s_waitcnt lgkmcnt(0)
	v_mfma_f32_32x32x16_bf16 v[32:47], v[2:5], v[6:9], v[32:47]
	v_add_u32_e32 v1, 0xffffde00, v1
	s_andn2_b64 vcc, exec, s[8:9]
	s_cbranch_vccnz .LBB0_489
	s_mov_b64 s[94:95], 0x100
	s_mov_b64 s[96:97], 0x2000
